# P1 stagger: WGs with 4 tiles sleep ~17us at GEMM1 start so their epilogues interleave with the 5-tile WGs
# speedup vs baseline: 1.0028x; 1.0025x over previous
; #define LAS __attribute__((address_space(3)))
; #define PG8_WAIT_V(n) asm volatile("s_waitcnt vmcnt(" #n ")" ::: "memory")
; #define PG8_BAR __builtin_amdgcn_s_barrier()
; template <class Epi>
; __device__ __forceinline__ void gemm_phase(LAS unsigned char* lds, const Gemm g, const StaticOrder& S, const Epi& E) {
;     const int tid = threadIdx.x, wid = __builtin_amdgcn_readfirstlane(tid >> 6), lane = tid & 63, wr = wid >> 2, wc = wid & 3, fr = lane & 15, fq = lane >> 4;
;     const int K = g.K, nt = K / BK;
;     unsigned voffA[2], voffB[2];
; #pragma unroll
;     for (int i = 0; i < 2; ++i) { int R, C; stage_rc(tid * 16 + i * 8192, R, C); const int Rb = Epi::PERM ? ((R & ~31) + perm32(R & 31)) : R;
;         voffA[i] = (unsigned)(R * K + C) * 2u; voffB[i] = (unsigned)(Rb * K + C) * 2u; }
;     const size_t kstep = (size_t)(BK * 2);
;     const size_t hstep = (size_t)HALF * K * 2;
;     const size_t tstep = 2 * hstep;
;     const unsigned ldsw = (unsigned)wid * 1024u;
;     const int aoff = lds_byte(wr * 64 + fr, fq * 8), boff = lds_byte(wc * 32 + fr, fq * 8);
;     ...
;     Unit cur, nxt; int ui = 0;
;     if (!S.next(0, cur)) return;
;     f32x4 acc[2][2][4][2];
; #pragma unroll
;     for (int a = 0; a < 2; ++a)
; #pragma unroll
;         for (int b = 0; b < 2; ++b)
; #pragma unroll
;             for (int m = 0; m < 4; ++m)
; #pragma unroll
;                 for (int n = 0; n < 2; ++n) acc[a][b][m][n] = (f32x4){0.f, 0.f, 0.f, 0.f};
;     bf16x8 At[4][2], B0[2][2], B1[2][2];
;     const char* cA = (const char*)g.A + (size_t)cur.pm * tstep; const char* cB = (const char*)g.Bt + (size_t)cur.pn * tstep;
;     PG8_STAGE(PG8_SB(0, 0), cB, voffB); PG8_STAGE(PG8_SA(0, 0), cA, voffA); PG8_STAGE(PG8_SB(0, 1), cB + hstep, voffB); PG8_STAGE(PG8_SA(0, 1), cA + hstep, voffA);
;     if (wr == 1) PG8_BAR;
;     PG8_WAIT_V(4); PG8_BAR;
;     PG8_STAGE(PG8_SB(1, 0), cB + kstep, voffB); PG8_STAGE(PG8_SA(1, 0), cA + kstep, voffA); PG8_STAGE(PG8_SB(1, 1), cB + hstep + kstep, voffB);
;     PG8_WAIT_V(6); PG8_BAR;
; __global__ void __launch_bounds__(512, 2) fwd(Params P) {
;     ...
;     if (IN(1)) for (int rep_ = 0; rep_ < NREP(1); ++rep_) { pg8::Gemm g{(const bf16_t*)(ws + O_XB), (const bf16_t*)(ws + O_WINT), MP, NPROJ, D}; pg8::StaticOrder S; S.init(MP, NPROJ, gridDim.x, blockIdx.x, GREP1);
;         EpiIn E{(bf16_t*)(ws + O_PROJ)}; pg8::gemm_phase<EpiIn>((LAS unsigned char*)shm, g, S, E);
.LBB0_124:
	s_cmp_lt_i32 s14, 2
	s_cselect_b64 s[0:1], -1, 0
	s_cmp_gt_i32 s15, 1
	s_cselect_b64 s[2:3], -1, 0
	s_and_b64 s[0:1], s[0:1], s[2:3]
	s_andn2_b64 vcc, exec, s[0:1]
	s_cbranch_vccnz .LBB0_289
	s_cmpk_lt_u32 s94, 0xa4
	s_cbranch_scc1 .Lstag1_done
	s_movk_i32 s0, 5
.Lstag1_loop:
	s_sleep 127
	s_add_i32 s0, s0, -1
	s_cmp_lg_u32 s0, 0
	s_cbranch_scc1 .Lstag1_loop
.Lstag1_done:
	s_add_u32 s6, s12, 0x2100000
	s_addc_u32 s7, s13, 0
	v_lshrrev_b32_e32 v148, 3, v214
	v_and_b32_e32 v150, 15, v214
	s_cmpk_gt_i32 s94, 0x4a3
	v_lshrrev_b32_e32 v149, 4, v214
	s_movk_i32 s0, 0x60
	v_readfirstlane_b32 s28, v214
	s_cbranch_scc1 .LBB0_141
	v_lshrrev_b32_e32 v2, 1, v214
	v_and_b32_e32 v11, 24, v2
	v_lshrrev_b32_e32 v2, 5, v214
	v_lshlrev_b32_e32 v0, 4, v214
	v_and_b32_e32 v1, 32, v214
	v_and_b32_e32 v2, 4, v2
	v_bfe_u32 v3, v214, 2, 2
	v_bfe_u32 v10, v214, 2, 4
	v_bitop3_b32 v8, v0, v1, 48 bitop3:0x6c
	v_and_b32_e32 v9, 64, v214
	v_or3_b32 v2, v2, v3, v11
	s_movk_i32 s1, 0x70
	v_add_u32_e32 v12, 0x2000, v0
	v_or_b32_e32 v1, v8, v9
	v_and_or_b32 v3, v148, s1, v10
	v_and_or_b32 v4, v148, s0, v2
	v_lshrrev_b32_e32 v0, 7, v12
	s_movk_i32 s0, 0xf0
	v_lshl_or_b32 v128, v3, 12, v1
	v_and_or_b32 v3, v0, s0, v10
	s_movk_i32 s0, 0xe0
	v_and_or_b32 v0, v0, s0, v2
	s_mul_hi_i32 s0, s94, 0x6e5478ad
	s_lshr_b32 s1, s0, 31
	s_ashr_i32 s0, s0, 9
	s_add_i32 s0, s0, s1
	s_mulk_i32 s0, 0x4a4
	s_sub_i32 s0, s94, s0
	s_bfe_u32 s1, s0, 0x3001c
	s_add_i32 s1, s0, s1
	s_sext_i32_i16 s2, s1
	s_and_b32 s1, s1, 0xfff8
	s_sub_i32 s0, s0, s1
	s_lshr_b32 s4, s28, 6
	s_mul_i32 s5, s0, 0x94
	s_lshr_b32 s3, s28, 8
	s_lshl_b32 s29, s4, 10
	s_ashr_i32 s2, s2, 3
	s_mul_i32 s1, s0, 0x95
	s_add_i32 s5, s5, 4
	s_sext_i32_i16 s0, s0
	s_cmp_lt_i32 s0, 4
	s_cselect_b32 s0, s1, s5
	s_add_i32 s0, s0, s2
	s_sext_i32_i16 s1, s0
	s_mulk_i32 s1, 0xe39
	s_lshr_b32 s2, s1, 31
	s_ashr_i32 s1, s1, 20
	s_add_i32 s1, s1, s2
	s_lshl_b32 s5, s1, 3
	s_sub_i32 s2, 33, s5
	s_mulk_i32 s1, 0x120
	s_min_u32 s8, s2, 8
	s_sub_i32 s9, s0, s1
	v_lshl_or_b32 v132, v3, 12, v1
	s_sext_i32_i16 s0, s9
	v_cvt_f32_ubyte0_e32 v3, s8
	v_lshl_or_b32 v130, v4, 12, v1
	v_cvt_f32_i32_e32 v2, s0
	v_rcp_iflag_f32_e32 v4, v3
	v_lshl_or_b32 v134, v0, 12, v1
	s_ashr_i32 s0, s0, 30
	s_or_b32 s2, s0, 1
	v_mul_f32_e32 v0, v2, v4
	v_trunc_f32_e32 v0, v0
	v_fma_f32 v1, -v0, v3, v2
	v_cvt_i32_f32_e32 v0, v0
	v_cmp_ge_f32_e64 s[0:1], |v1|, v3
	s_and_b64 s[0:1], s[0:1], exec
	s_cselect_b32 s0, s2, 0
	v_readfirstlane_b32 s1, v0
	s_add_i32 s2, s1, s0
	s_mul_i32 s0, s2, s8
	s_sub_i32 s0, s9, s0
	s_sext_i32_i16 s0, s0
	s_add_i32 s16, s5, s0
	s_ashr_i32 s17, s16, 31
	s_bfe_i64 s[8:9], s[2:3], 0x100000
	s_lshl_b64 s[0:1], s[16:17], 20
	s_lshl_b64 s[8:9], s[8:9], 20
	s_add_u32 s24, s6, s8
	s_addc_u32 s25, s7, s9
	s_add_i32 s17, s29, 0
	s_add_i32 m0, s17, 0x10000
	v_mov_b32_e32 v131, 0
	global_load_lds_dwordx4 v130, s[24:25]
	s_add_i32 m0, s17, 0x12000
	s_add_u32 s22, s12, s0
	global_load_lds_dwordx4 v134, s[24:25]
	s_addc_u32 s23, s13, s1
	s_mov_b32 m0, s17
	s_add_i32 s30, s17, 0x2000
	global_load_lds_dwordx4 v128, s[22:23]
	s_mov_b32 m0, s30
	s_add_u32 s0, s24, 0x80000
	global_load_lds_dwordx4 v132, s[22:23]
	s_addc_u32 s1, s25, 0
	s_add_i32 m0, s17, 0x14000
	v_mov_b32_e32 v135, v131
	global_load_lds_dwordx4 v130, s[0:1]
	s_add_i32 m0, s17, 0x16000
	v_mov_b32_e32 v129, v131
	global_load_lds_dwordx4 v134, s[0:1]
	s_add_u32 s0, s22, 0x80000
	s_addc_u32 s1, s23, 0
	s_add_i32 s31, s17, 0x4000
	s_mov_b32 m0, s31
	s_add_i32 s33, s17, 0x6000
	global_load_lds_dwordx4 v128, s[0:1]
	s_mov_b32 m0, s33
	v_mov_b32_e32 v133, v131
	global_load_lds_dwordx4 v132, s[0:1]
	s_mov_b32 s34, 0
	v_lshl_add_u64 v[6:7], s[24:25], 0, v[130:131]
	v_lshl_add_u64 v[4:5], s[24:25], 0, v[134:135]
	v_lshl_add_u64 v[2:3], s[22:23], 0, v[128:129]
	s_cmp_lg_u32 s3, 1
	v_lshl_add_u64 v[0:1], s[22:23], 0, v[132:133]
	s_cbranch_scc1 .LBB0_128
	s_barrier
